# attention sample item: q/k norm gains, rope entries and new V row loads issued together with the first data loads
# speedup vs baseline: 1.0034x; 1.0034x over previous
.LBB0_191:
	s_or_b64 exec, exec, s[22:23]
	s_add_i32 s24, s26, 0x4000
	s_ashr_i32 s25, s24, 31
	s_and_saveexec_b64 s[22:23], s[6:7]
	s_xor_b64 s[22:23], exec, s[22:23]
	s_cbranch_execz .LBB0_196
	s_and_saveexec_b64 s[28:29], s[8:9]
	s_cbranch_execz .LBB0_195
	s_lshl_b64 s[30:31], s[24:25], 11
	s_add_u32 s30, s60, s30
	s_addc_u32 s31, s61, s31
	s_lshl_b32 s35, s34, 8
	s_add_u32 s30, s30, s35
	s_addc_u32 s31, s31, 0
	v_lshlrev_b32_e32 v192, 2, v32
	global_load_dword v58, v192, s[30:31]
	global_load_dword v59, v192, s[30:31] offset:128
	s_load_dwordx2 s[36:37], s[0:1], 0x98
	global_load_dword v174, v[52:53], off
	global_load_dword v175, v[54:55], off
	global_load_dword v170, v192, s[30:31] offset:1024
	global_load_dword v171, v192, s[30:31] offset:1152
	s_waitcnt lgkmcnt(0)
	global_load_dword v172, v192, s[36:37]
	global_load_dword v173, v192, s[36:37] offset:128
	s_waitcnt vmcnt(6)
	v_pk_mul_f32 v[60:61], v[58:59], v[58:59]
	s_nop 0
	v_add_f32_e32 v57, v60, v61
	ds_bpermute_b32 v60, v74, v57
	s_waitcnt lgkmcnt(0)
	v_add_f32_e32 v57, v57, v60
	ds_bpermute_b32 v60, v75, v57
	s_waitcnt lgkmcnt(0)
	v_add_f32_e32 v57, v57, v60
	ds_bpermute_b32 v60, v76, v57
	s_waitcnt lgkmcnt(0)
	v_add_f32_e32 v57, v57, v60
	ds_bpermute_b32 v60, v77, v57
	s_waitcnt lgkmcnt(0)
	v_add_f32_e32 v57, v57, v60
	ds_bpermute_b32 v60, v78, v57
	s_waitcnt lgkmcnt(0)
	v_add_f32_e32 v57, v57, v60
	v_fmamk_f32 v57, v57, 0x3c800000, v226
	v_cmp_gt_f32_e32 vcc, s87, v57
	v_mul_f32_e32 v60, 0x4b800000, v57
	s_nop 0
	v_cndmask_b32_e32 v57, v57, v60, vcc
	v_rsq_f32_e32 v57, v57
	s_nop 0
	v_mul_f32_e32 v60, 0x45800000, v57
	v_cndmask_b32_e32 v57, v57, v60, vcc
	s_andn2_b64 vcc, exec, s[76:77]
	s_waitcnt vmcnt(0)
	v_mul_f32_e32 v60, v172, v57
	v_mul_f32_e32 v58, v58, v60
	v_mul_f32_e32 v57, v173, v57
	v_mul_f32_e32 v59, v59, v57
	v_mul_f32_e32 v57, v175, v59
	v_fma_f32 v57, v174, v58, -v57
	v_mul_f32_e32 v58, v175, v58
	v_fmac_f32_e32 v58, v174, v59
	v_add_u32_e32 v61, 0x8400, v64
	ds_write2_b32 v61, v57, v58 offset0:188 offset1:220
	ds_write2_b32 v92, v170, v171 offset0:192 offset1:224
	s_cbranch_vccnz .LBB0_195
	s_load_dwordx2 s[30:31], s[0:1], 0xd0
	s_lshl_b32 s35, s34, 6
	s_lshl_b32 s35, s35, 2
	s_lshl_b64 s[36:37], s[26:27], 17
	s_or_b32 s35, s36, s35
	s_or_b32 s35, s35, 0x1fc00
	s_waitcnt lgkmcnt(0)
	s_add_u32 s30, s30, s35
	s_addc_u32 s31, s31, s37
	v_lshl_add_u64 v[62:63], s[30:31], 0, v[192:193]
	s_mov_b64 s[30:31], 0xc580000
	v_add_co_u32_e32 v96, vcc, 0xc580000, v62
	v_lshl_add_u64 v[94:95], v[62:63], 0, s[30:31]
	s_nop 0
	v_addc_co_u32_e32 v97, vcc, 0, v63, vcc
	s_mov_b64 s[30:31], 0xd580000
	global_store_dword v[96:97], v57, off
	global_store_dword v[94:95], v58, off offset:128
	v_lshl_add_u64 v[94:95], v[62:63], 0, s[30:31]
	v_add_co_u32_e32 v62, vcc, 0xd580000, v62
	s_nop 1
	v_addc_co_u32_e32 v63, vcc, 0, v63, vcc
	global_store_dword v[62:63], v170, off
	global_store_dword v[94:95], v171, off offset:128

.LBB0_196:
	s_andn2_saveexec_b64 s[22:23], s[22:23]
	s_cbranch_execz .LBB0_198
	s_lshl_b64 s[28:29], s[24:25], 11
	v_readlane_b32 s30, v254, 36
	v_lshl_add_u32 v58, s34, 8, v65
	v_readlane_b32 s31, v254, 37
	s_add_u32 s28, s30, s28
	v_ashrrev_i32_e32 v59, 31, v58
	s_addc_u32 s29, s31, s29
	v_lshl_add_u64 v[58:59], v[58:59], 1, s[28:29]
	v_lshlrev_b32_e32 v192, 1, v32
	v_lshl_add_u64 v[58:59], v[58:59], 0, v[192:193]
	global_load_ushort v57, v[58:59], off
	s_nop 0
	global_load_ushort v58, v[58:59], off offset:64
	global_load_dword v172, v[34:35], off
	global_load_dword v173, v[34:35], off offset:128
	global_load_dword v174, v[52:53], off
	global_load_dword v175, v[54:55], off
	s_waitcnt vmcnt(4)
	v_lshlrev_b32_e32 v59, 16, v58
	v_lshlrev_b32_e32 v58, 16, v57
	v_pk_mul_f32 v[60:61], v[58:59], v[58:59]
	s_nop 0
	v_add_f32_e32 v57, v60, v61
	ds_bpermute_b32 v60, v74, v57
	s_waitcnt lgkmcnt(0)
	v_add_f32_e32 v57, v57, v60
	ds_bpermute_b32 v60, v75, v57
	s_waitcnt lgkmcnt(0)
	v_add_f32_e32 v57, v57, v60
	ds_bpermute_b32 v60, v76, v57
	s_waitcnt lgkmcnt(0)
	v_add_f32_e32 v57, v57, v60
	ds_bpermute_b32 v60, v77, v57
	s_waitcnt lgkmcnt(0)
	v_add_f32_e32 v57, v57, v60
	ds_bpermute_b32 v60, v78, v57
	s_waitcnt lgkmcnt(0)
	v_add_f32_e32 v57, v57, v60
	v_fmamk_f32 v57, v57, 0x3c800000, v226
	v_cmp_gt_f32_e32 vcc, s87, v57
	v_mul_f32_e32 v60, 0x4b800000, v57
	s_nop 0
	v_cndmask_b32_e32 v57, v57, v60, vcc
	v_rsq_f32_e32 v57, v57
	s_nop 0
	v_mul_f32_e32 v60, 0x45800000, v57
	v_cndmask_b32_e32 v57, v57, v60, vcc
	s_waitcnt vmcnt(0)
	v_mul_f32_e32 v60, v172, v57
	v_mul_f32_e32 v58, v60, v58
	v_mul_f32_e32 v57, v173, v57
	v_mul_f32_e32 v57, v57, v59
	v_mul_f32_e32 v61, v175, v57
	v_fma_f32 v61, v174, v58, -v61
	v_mul_f32_e32 v58, v175, v58
	v_fmac_f32_e32 v58, v174, v57
	v_mul_f32_e32 v61, 0x3e000000, v61
	v_mul_f32_e32 v57, 0x3e000000, v58
	ds_write2_b32 v66, v61, v57 offset1:32
